# speedup vs baseline: 1.0073x; 1.0073x over previous
; __device__ __forceinline__ void phase_hyena_mfma(const Params& p, int l, const int tidx, int first_block, int nblocks) {
;     ...
;   for (int c = bid; c < 512; c += nblocks) {
;     __syncthreads();
; #pragma unroll
;     for (int i = 0; i < 2; i++) {
;       int q = tidx + NT * i;
;       *(u32x4*)(sG + q * 8) = *(const u32x4*)(GT + (size_t)c * 8192 + q * 8);
;     }
; #pragma unroll
;     for (int i = 0; i < 8; i++) {
;       int q = tidx + NT * i;
;       int b = q >> 9, off = (q & 511) * 8;
;       *(u32x4*)(sZ + b * ZS + 64 + off) = *(const u32x4*)(ZT + (size_t)c * T + b * SEQ + off);
;     }
;     if (tidx < 128) {
;       int b = tidx >> 4, k = tidx & 15;
;       *(u32x4*)(sZ + b * ZS + ((k < 8) ? k * 8 : (4160 + (k - 8) * 8))) = u32x4{0u, 0u, 0u, 0u};
;     }
;     __syncthreads();
;     const int Tt0 = w * 8;
;     f32x4 acc[4][4];
; #pragma unroll
;     for (int i = 0; i < 4; i++)
; #pragma unroll
;       for (int j = 0; j < 4; j++) acc[i][j] = f32x4{0.f, 0.f, 0.f, 0.f};
;     const bf16_t* zrow = sZ + (l15 & 7) * ZS + 64 + 64 * (Tt0 + (l15 >> 3)) + quad * 8;
; #pragma unroll 1
;     for (int D = Tt0 - 63; D <= Tt0 + 7; D++) {
; #pragma unroll
;       for (int ks = 0; ks < 2; ks++) {
;         bf16x8 af[4];
; #pragma unroll
;         for (int it = 0; it < 4; it++) {
;           int e0 = 4095 - 64 * D + 32 * ks - 16 * it + 8 * quad - l15;
;           const unsigned* gp = (const unsigned*)sG + (e0 >> 1);
;           unsigned sh = (e0 & 1) * 16;
;           unsigned w0 = gp[0], w1 = gp[1], w2 = gp[2], w3 = gp[3], w4 = gp[4];
;           u32x4 fr;
;           fr[0] = __builtin_amdgcn_alignbit(w1, w0, sh);
;           fr[1] = __builtin_amdgcn_alignbit(w2, w1, sh);
;           fr[2] = __builtin_amdgcn_alignbit(w3, w2, sh);
;           fr[3] = __builtin_amdgcn_alignbit(w4, w3, sh);
;           af[it] = __builtin_bit_cast(bf16x8, fr);
;         }
.LBB0_174:
	s_lshl_b64 s[14:15], s[0:1], 14
	v_readlane_b32 s16, v251, 39
	s_add_u32 s14, s16, s14
	v_readlane_b32 s16, v251, 40
	s_addc_u32 s15, s16, s15
	v_lshl_add_u64 v[2:3], v[88:89], 1, s[14:15]
	s_barrier
	global_load_dwordx4 v[8:11], v[2:3], off
	v_lshl_add_u64 v[2:3], v[92:93], 1, s[14:15]
	s_lshl_b64 s[14:15], s[0:1], 16
	s_waitcnt vmcnt(0)
	ds_write_b128 v129, v[8:11]
	global_load_dwordx4 v[8:11], v[2:3], off
	v_lshl_add_u64 v[2:3], v[90:91], 0, s[14:15]
	v_lshl_add_u64 v[110:111], v[94:95], 1, v[2:3]
	v_lshl_add_u64 v[112:113], v[96:97], 1, v[2:3]
	v_lshl_add_u64 v[116:117], v[98:99], 1, v[2:3]
	v_lshl_add_u64 v[114:115], v[100:101], 1, v[2:3]
	v_lshl_add_u64 v[118:119], v[102:103], 1, v[2:3]
	v_lshl_add_u64 v[120:121], v[104:105], 1, v[2:3]
	v_lshl_add_u64 v[124:125], v[106:107], 1, v[2:3]
	v_lshl_add_u64 v[122:123], v[108:109], 1, v[2:3]
	s_waitcnt vmcnt(0)
	ds_write_b128 v130, v[8:11]
	global_load_dwordx4 v[8:11], v[110:111], off
	s_waitcnt vmcnt(0)
	ds_write_b128 v128, v[8:11] offset:128
	global_load_dwordx4 v[8:11], v[112:113], off
	s_waitcnt vmcnt(0)
	ds_write_b128 v131, v[8:11] offset:128
	global_load_dwordx4 v[8:11], v[116:117], off
	s_waitcnt vmcnt(0)
	ds_write_b128 v132, v[8:11] offset:128
	global_load_dwordx4 v[8:11], v[114:115], off
	s_waitcnt vmcnt(0)
	ds_write_b128 v133, v[8:11] offset:128
	global_load_dwordx4 v[8:11], v[118:119], off
	s_waitcnt vmcnt(0)
	ds_write_b128 v134, v[8:11] offset:128
	global_load_dwordx4 v[8:11], v[120:121], off
	s_waitcnt vmcnt(0)
	ds_write_b128 v135, v[8:11] offset:128
	global_load_dwordx4 v[8:11], v[124:125], off
	s_waitcnt vmcnt(0)
	ds_write_b128 v136, v[8:11] offset:128
	global_load_dwordx4 v[8:11], v[122:123], off
	s_waitcnt vmcnt(0)
	ds_write_b128 v137, v[8:11] offset:128
	s_and_saveexec_b64 s[14:15], s[10:11]
	ds_write_b128 v126, v[4:7]
	s_or_b64 exec, exec, s[14:15]
	v_mov_b32_e32 v2, v1
	v_mov_b32_e32 v3, v1
	v_mov_b32_e32 v0, v1
	v_mov_b64_e32 v[70:71], v[2:3]
	v_mov_b64_e32 v[66:67], v[2:3]
	v_mov_b64_e32 v[62:63], v[2:3]
	v_mov_b64_e32 v[58:59], v[2:3]
	v_mov_b64_e32 v[54:55], v[2:3]
	v_mov_b64_e32 v[50:51], v[2:3]
	v_mov_b64_e32 v[46:47], v[2:3]
	v_mov_b64_e32 v[42:43], v[2:3]
	v_mov_b64_e32 v[38:39], v[2:3]
	v_mov_b64_e32 v[34:35], v[2:3]
	v_mov_b64_e32 v[30:31], v[2:3]
	v_mov_b64_e32 v[26:27], v[2:3]
	v_mov_b64_e32 v[22:23], v[2:3]
	v_mov_b64_e32 v[18:19], v[2:3]
	v_mov_b64_e32 v[14:15], v[2:3]
	v_mov_b64_e32 v[10:11], v[2:3]
	v_mov_b64_e32 v[68:69], v[0:1]
	v_mov_b64_e32 v[64:65], v[0:1]
	v_mov_b64_e32 v[60:61], v[0:1]
	v_mov_b64_e32 v[56:57], v[0:1]
	v_mov_b64_e32 v[52:53], v[0:1]
	v_mov_b64_e32 v[48:49], v[0:1]
	v_mov_b64_e32 v[44:45], v[0:1]
	v_mov_b64_e32 v[40:41], v[0:1]
	v_mov_b64_e32 v[36:37], v[0:1]
	v_mov_b64_e32 v[32:33], v[0:1]
	v_mov_b64_e32 v[28:29], v[0:1]
	v_mov_b64_e32 v[24:25], v[0:1]
	v_mov_b64_e32 v[20:21], v[0:1]
	v_mov_b64_e32 v[16:17], v[0:1]
	v_mov_b64_e32 v[12:13], v[0:1]
	v_mov_b64_e32 v[8:9], v[0:1]
	s_waitcnt lgkmcnt(0)
	s_barrier
	s_and_saveexec_b64 s[14:15], s[12:13]
	s_cbranch_execz .LBB0_173
	v_mov_b32_e32 v2, v1
	v_mov_b32_e32 v3, v1
	v_mov_b32_e32 v0, v1
	v_mov_b64_e32 v[10:11], v[2:3]
	v_mov_b64_e32 v[14:15], v[2:3]
	v_mov_b64_e32 v[18:19], v[2:3]
	v_mov_b64_e32 v[22:23], v[2:3]
	v_mov_b64_e32 v[26:27], v[2:3]
	v_mov_b64_e32 v[30:31], v[2:3]
	v_mov_b64_e32 v[34:35], v[2:3]
	v_mov_b64_e32 v[38:39], v[2:3]
	v_mov_b64_e32 v[42:43], v[2:3]
	v_mov_b64_e32 v[46:47], v[2:3]
	v_mov_b64_e32 v[50:51], v[2:3]
	v_mov_b64_e32 v[54:55], v[2:3]
	v_mov_b64_e32 v[58:59], v[2:3]
	v_mov_b64_e32 v[62:63], v[2:3]
	v_mov_b64_e32 v[66:67], v[2:3]
	v_mov_b64_e32 v[70:71], v[2:3]
	s_movk_i32 s28, 0x46
	s_mov_b64 s[16:17], 0
	v_mov_b32_e32 v143, v141
	v_mov_b32_e32 v144, v140
	v_mov_b32_e32 v145, v139
	v_mov_b32_e32 v146, v138
	v_mov_b64_e32 v[8:9], v[0:1]
	v_mov_b64_e32 v[12:13], v[0:1]
	v_mov_b64_e32 v[16:17], v[0:1]
	v_mov_b64_e32 v[20:21], v[0:1]
	v_mov_b64_e32 v[24:25], v[0:1]
	v_mov_b64_e32 v[28:29], v[0:1]
	v_mov_b64_e32 v[32:33], v[0:1]
	v_mov_b64_e32 v[36:37], v[0:1]
	v_mov_b64_e32 v[40:41], v[0:1]
	v_mov_b64_e32 v[44:45], v[0:1]
	v_mov_b64_e32 v[48:49], v[0:1]
	v_mov_b64_e32 v[52:53], v[0:1]
	v_mov_b64_e32 v[56:57], v[0:1]
	v_mov_b64_e32 v[60:61], v[0:1]
	v_mov_b64_e32 v[64:65], v[0:1]
	v_mov_b64_e32 v[68:69], v[0:1]
	v_lshlrev_b32_e32 v236, 1, v141
	v_and_b32_e32 v236, -4, v236
	v_add_u32_e32 v236, s69, v236
	v_add_u32_e32 v236, 0xffffff60, v236
	ds_read2_b32 v[180:181], v236 offset0:40 offset1:41
	ds_read2_b32 v[182:183], v236 offset0:42 offset1:43
	ds_read_b32 v184, v236 offset:176
	ds_read2_b32 v[186:187], v236 offset0:32 offset1:33
	ds_read2_b32 v[188:189], v236 offset0:34 offset1:35
	ds_read_b32 v190, v236 offset:144
	s_waitcnt lgkmcnt(0)
	v_alignbit_b32 v170, v181, v180, v140
	v_alignbit_b32 v171, v182, v181, v140
	v_alignbit_b32 v172, v183, v182, v140
	v_alignbit_b32 v173, v184, v183, v140
	v_alignbit_b32 v174, v187, v186, v140
	v_alignbit_b32 v175, v188, v187, v140
	v_alignbit_b32 v176, v189, v188, v140
	v_alignbit_b32 v177, v190, v189, v140
	s_branch .LBB0_179

; __device__ __forceinline__ void phase_hyena_mfma(const Params& p, int l, const int tidx, int first_block, int nblocks) {
;     ...
;     for (int D = Tt0 - 63; D <= Tt0 + 7; D++) {
; #pragma unroll
;       for (int ks = 0; ks < 2; ks++) {
;         bf16x8 af[4];
; #pragma unroll
;         for (int it = 0; it < 4; it++) {
;           int e0 = 4095 - 64 * D + 32 * ks - 16 * it + 8 * quad - l15;
;           const unsigned* gp = (const unsigned*)sG + (e0 >> 1);
;           unsigned sh = (e0 & 1) * 16;
;           unsigned w0 = gp[0], w1 = gp[1], w2 = gp[2], w3 = gp[3], w4 = gp[4];
;           u32x4 fr;
;           fr[0] = __builtin_amdgcn_alignbit(w1, w0, sh);
;           fr[1] = __builtin_amdgcn_alignbit(w2, w1, sh);
;           fr[2] = __builtin_amdgcn_alignbit(w3, w2, sh);
;           fr[3] = __builtin_amdgcn_alignbit(w4, w3, sh);
;           af[it] = __builtin_bit_cast(bf16x8, fr);
;         }
; #pragma unroll
;         for (int nt = 0; nt < 4; nt++) {
;           int stlo = Tt0 + 2 * nt - D;
;           if (stlo >= -1 && stlo <= 63) {
;             bf16x8 bfv = *(const bf16x8*)(zrow + 64 * (2 * nt - D) + ks * 32);
; #pragma unroll
;             for (int it = 0; it < 4; it++) acc[it][nt] = __builtin_amdgcn_mfma_f32_16x16x32_bf16(af[it], bfv, acc[it][nt], 0, 0, 0);
;           }
;         }
;       }
.LBB0_179:
	ds_read2_b32 v[180:181], v236 offset0:24 offset1:25
	ds_read2_b32 v[182:183], v236 offset0:26 offset1:27
	ds_read_b32 v184, v236 offset:112
	ds_read2_b32 v[186:187], v236 offset0:16 offset1:17
	ds_read2_b32 v[188:189], v236 offset0:18 offset1:19
	ds_read_b32 v190, v236 offset:80
	ds_read2_b32 v[192:193], v236 offset0:8 offset1:9
	ds_read2_b32 v[194:195], v236 offset0:10 offset1:11
	ds_read_b32 v196, v236 offset:48
	ds_read2_b32 v[198:199], v236 offset0:0 offset1:1
	ds_read2_b32 v[200:201], v236 offset0:2 offset1:3
	ds_read_b32 v202, v236 offset:16
	s_add_i32 s18, s28, -6
	s_cmpk_lt_u32 s18, 0x41
	s_cbranch_scc0 .Lhy_nob0
	ds_read_b128 v[204:207], v146
	ds_read_b128 v[208:211], v146 offset:64
.Lhy_nob0:
	s_add_i32 s18, s28, -4
	s_cmpk_lt_u32 s18, 0x41
	s_cbranch_scc0 .Lhy_nob1
	ds_read_b128 v[212:215], v146 offset:256
	ds_read_b128 v[216:219], v146 offset:320
.Lhy_nob1:
	s_add_i32 s18, s28, -2
	s_cmpk_lt_u32 s18, 0x41
	s_cbranch_scc0 .Lhy_nob2
	ds_read_b128 v[220:223], v146 offset:512
	ds_read_b128 v[224:227], v146 offset:576
.Lhy_nob2:
	s_add_i32 s18, s28, 0
	s_cmpk_lt_u32 s18, 0x41
	s_cbranch_scc0 .Lhy_nob3
	ds_read_b128 v[228:231], v146 offset:768
	ds_read_b128 v[232:235], v146 offset:832
.Lhy_nob3:
	v_subrev_u32_e32 v143, 64, v143
	v_add_u32_e32 v236, 0xffffff80, v236
	s_waitcnt lgkmcnt(0)
	v_alignbit_b32 v72, v181, v180, v144
	v_alignbit_b32 v73, v182, v181, v144
	v_alignbit_b32 v74, v183, v182, v144
	v_alignbit_b32 v75, v184, v183, v144
	v_alignbit_b32 v76, v187, v186, v144
	v_alignbit_b32 v77, v188, v187, v144
	v_alignbit_b32 v78, v189, v188, v144
	v_alignbit_b32 v79, v190, v189, v144
	v_alignbit_b32 v80, v193, v192, v144
	v_alignbit_b32 v81, v194, v193, v144
	v_alignbit_b32 v82, v195, v194, v144
	v_alignbit_b32 v83, v196, v195, v144
	v_alignbit_b32 v84, v199, v198, v144
	v_alignbit_b32 v85, v200, v199, v144
	v_alignbit_b32 v86, v201, v200, v144
	v_alignbit_b32 v87, v202, v201, v144
	s_add_i32 s18, s28, -6
	s_cmpk_lt_u32 s18, 0x41
	s_cbranch_scc0 .Lhy_nom0
	v_mfma_f32_16x16x32_bf16 v[68:71], v[72:75], v[204:207], v[68:71]
	v_mfma_f32_16x16x32_bf16 v[52:55], v[76:79], v[204:207], v[52:55]
	v_mfma_f32_16x16x32_bf16 v[36:39], v[80:83], v[204:207], v[36:39]
	v_mfma_f32_16x16x32_bf16 v[20:23], v[84:87], v[204:207], v[20:23]
	v_mfma_f32_16x16x32_bf16 v[68:71], v[170:173], v[208:211], v[68:71]
	v_mfma_f32_16x16x32_bf16 v[52:55], v[174:177], v[208:211], v[52:55]
	v_mfma_f32_16x16x32_bf16 v[36:39], v[72:75], v[208:211], v[36:39]
	v_mfma_f32_16x16x32_bf16 v[20:23], v[76:79], v[208:211], v[20:23]
.Lhy_nom0:
	s_add_i32 s18, s28, -4
	s_cmpk_lt_u32 s18, 0x41
	s_cbranch_scc0 .Lhy_nom1
	v_mfma_f32_16x16x32_bf16 v[64:67], v[72:75], v[212:215], v[64:67]
	v_mfma_f32_16x16x32_bf16 v[48:51], v[76:79], v[212:215], v[48:51]
	v_mfma_f32_16x16x32_bf16 v[32:35], v[80:83], v[212:215], v[32:35]
	v_mfma_f32_16x16x32_bf16 v[16:19], v[84:87], v[212:215], v[16:19]
	v_mfma_f32_16x16x32_bf16 v[64:67], v[170:173], v[216:219], v[64:67]
	v_mfma_f32_16x16x32_bf16 v[48:51], v[174:177], v[216:219], v[48:51]
	v_mfma_f32_16x16x32_bf16 v[32:35], v[72:75], v[216:219], v[32:35]
	v_mfma_f32_16x16x32_bf16 v[16:19], v[76:79], v[216:219], v[16:19]
.Lhy_nom1:
	s_add_i32 s18, s28, -2
	s_cmpk_lt_u32 s18, 0x41
	s_cbranch_scc0 .Lhy_nom2
	v_mfma_f32_16x16x32_bf16 v[60:63], v[72:75], v[220:223], v[60:63]
	v_mfma_f32_16x16x32_bf16 v[44:47], v[76:79], v[220:223], v[44:47]
	v_mfma_f32_16x16x32_bf16 v[28:31], v[80:83], v[220:223], v[28:31]
	v_mfma_f32_16x16x32_bf16 v[12:15], v[84:87], v[220:223], v[12:15]
	v_mfma_f32_16x16x32_bf16 v[60:63], v[170:173], v[224:227], v[60:63]
	v_mfma_f32_16x16x32_bf16 v[44:47], v[174:177], v[224:227], v[44:47]
	v_mfma_f32_16x16x32_bf16 v[28:31], v[72:75], v[224:227], v[28:31]
	v_mfma_f32_16x16x32_bf16 v[12:15], v[76:79], v[224:227], v[12:15]
.Lhy_nom2:
	s_add_i32 s18, s28, 0
	s_cmpk_lt_u32 s18, 0x41
	s_cbranch_scc0 .Lhy_nom3
	v_mfma_f32_16x16x32_bf16 v[56:59], v[72:75], v[228:231], v[56:59]
	v_mfma_f32_16x16x32_bf16 v[40:43], v[76:79], v[228:231], v[40:43]
	v_mfma_f32_16x16x32_bf16 v[24:27], v[80:83], v[228:231], v[24:27]
	v_mfma_f32_16x16x32_bf16 v[8:11], v[84:87], v[228:231], v[8:11]
	v_mfma_f32_16x16x32_bf16 v[56:59], v[170:173], v[232:235], v[56:59]
	v_mfma_f32_16x16x32_bf16 v[40:43], v[174:177], v[232:235], v[40:43]
	v_mfma_f32_16x16x32_bf16 v[24:27], v[72:75], v[232:235], v[24:27]
	v_mfma_f32_16x16x32_bf16 v[8:11], v[76:79], v[232:235], v[8:11]
.Lhy_nom3:
	v_mov_b64_e32 v[170:171], v[80:81]
	v_mov_b64_e32 v[172:173], v[82:83]
	v_mov_b64_e32 v[174:175], v[84:85]
	v_mov_b64_e32 v[176:177], v[86:87]
	s_branch .LBB0_178

; __device__ __forceinline__ void phase_mlstm_scan(const Params& p, const int tidx) {
;     ...
;   const int tid = tidx, lane = tid & 63, w = tid >> 6;
;   const int l15 = lane & 15, quad = lane >> 4;
;   bf16_t* sQ = (bf16_t*)smem_raw;
;   bf16_t* sK = sQ + 64 * QSTR;
;   bf16_t* sVt = sK + 64 * QSTR;
;   bf16_t* sKtw = sVt + 144 * LSTR;
;   bf16_t* sS = sKtw + 128 * LSTR;
;   bf16_t* sC = sS + 64 * LSTR;
;   float* s_b = (float*)(sC + 144 * QSTR);
;   float* s_lib = s_b + 64;
;   float* s_mt = s_lib + 64;
;   float* s_wint = s_mt + 64;
;   float* s_den = s_wint + 64;
;   const bf16_t* Qg = (const bf16_t*)(p.ws + WS_R1 + R1_Q);
;   const bf16_t* Kg = Qg + (size_t)T * 512;
;   const bf16_t* Vg = Kg + (size_t)T * 512;
;   const float* GSb = (const float*)(p.ws + WS_GS) + (size_t)((b * 4 + h) * 2 + dir) * 4096;
;   bf16_t* P = (bf16_t*)(p.ws + WS_P);
;   __syncthreads();
;   for (int e = tid; e < 144 * QSTR; e += NT) sC[e] = 0;
;   for (int e = tid; e < 144 * LSTR; e += NT) sVt[e] = 0;
;   __syncthreads();
;   if (tid < 64) sVt[128 * LSTR + tid] = 0x3F80;
;   f32x4 cacc[5];
; #pragma unroll
;   for (int i = 0; i < 5; i++) cacc[i] = f32x4{0.f, 0.f, 0.f, 0.f};
;   float mstate = -INFINITY;
;   u32x4 qv[2], kv[2], vv[2];
;   float gbc, glib, gpm;
;     ...
;   ML_LOAD(0);
.LBB0_203:
	s_or_b64 exec, exec, s[10:11]
	v_cmp_gt_i32_e32 vcc, 64, v150
	s_waitcnt lgkmcnt(0)
	s_barrier
	s_and_saveexec_b64 s[10:11], vcc
	v_lshl_add_u32 v0, v150, 1, 0
	v_mov_b32_e32 v2, 0x3f80
	ds_write_b16 v0, v2 offset:53248
	s_or_b64 exec, exec, s[10:11]
	v_and_b32_e32 v33, 63, v150
	v_lshlrev_b32_e32 v0, 9, v33
	v_readlane_b32 s10, v251, 47
	v_ashrrev_i32_e32 v38, 6, v150
	v_xor_b32_e32 v2, 0x1ffe00, v0
	v_readlane_b32 s11, v251, 48
	v_readlane_b32 s12, v251, 43
	v_readlane_b32 s13, v251, 44
	v_cndmask_b32_e64 v0, v2, v0, s[10:11]
	v_lshlrev_b32_e32 v2, 3, v38
	v_readlane_b32 s10, v253, 28
	v_add_u32_e32 v104, 64, v2
	v_readlane_b32 s11, v253, 29
	v_or_b32_e32 v0, s10, v0
	v_ashrrev_i32_e32 v3, 31, v2
	v_ashrrev_i32_e32 v105, 31, v104
	s_waitcnt vmcnt(14)
	v_lshl_add_u64 v[8:9], v[0:1], 0, v[2:3]
	v_readlane_b32 s10, v251, 41
	v_lshl_add_u64 v[18:19], v[0:1], 0, v[104:105]
	v_lshlrev_b64 v[8:9], 1, v[8:9]
	v_readlane_b32 s11, v251, 42
	v_lshlrev_b64 v[18:19], 1, v[18:19]
	v_lshlrev_b32_e32 v0, 2, v33
	v_lshl_add_u64 v[10:11], s[10:11], 0, v[8:9]
	s_waitcnt vmcnt(12)
	v_lshl_add_u64 v[24:25], s[10:11], 0, v[18:19]
	v_readlane_b32 s10, v251, 45
	v_readlane_b32 s11, v251, 46
	v_lshl_add_u64 v[16:17], s[50:51], 0, v[8:9]
	v_lshl_add_u64 v[12:13], s[12:13], 0, v[8:9]
	s_waitcnt vmcnt(11)
	v_lshl_add_u64 v[30:31], s[10:11], 0, v[0:1]
	v_add_co_u32_e32 v34, vcc, s14, v30
	v_lshl_add_u64 v[20:21], s[50:51], 0, v[18:19]
	s_nop 0
	v_addc_co_u32_e32 v35, vcc, 0, v31, vcc
	v_lshl_add_u64 v[28:29], s[12:13], 0, v[18:19]
	v_add_co_u32_e32 v36, vcc, s5, v30
	global_load_dwordx4 v[8:11], v[10:11], off
	s_nop 0
	global_load_dwordx4 v[12:15], v[12:13], off
	s_nop 0
	global_load_dwordx4 v[20:23], v[20:21], off
	s_nop 0
	global_load_dwordx4 v[24:27], v[24:25], off
	s_nop 0
	global_load_dwordx4 v[16:19], v[16:17], off
	s_nop 0
	global_load_dword v114, v0, s[10:11]
	v_addc_co_u32_e32 v37, vcc, 0, v31, vcc
	global_load_dwordx4 v[28:31], v[28:29], off
	s_nop 0
	global_load_dword v122, v[34:35], off
	global_load_dword v136, v[36:37], off
	v_mul_u32_u24_e32 v34, 0x88, v33
	v_ashrrev_i32_e32 v37, 3, v150
	v_and_b32_e32 v42, 48, v150
	v_and_b32_e32 v43, 3, v38
	v_readlane_b32 s17, v254, 24
	v_and_b32_e32 v32, 15, v150
	v_bfe_u32 v39, v150, 4, 2
	v_lshlrev_b32_e32 v35, 1, v34
	v_bfi_b32 v41, -16, v37, v150
	v_add_u32_e32 v34, 0, v42
	s_movk_i32 s5, 0x110
	v_lshl_add_u32 v44, v43, 6, s17
	v_lshlrev_b32_e32 v43, 4, v43
	v_lshlrev_b32_e32 v36, 5, v38
	v_mad_u64_u32 v[106:107], s[12:13], v41, s5, v[34:35]
	v_lshlrev_b32_e32 v41, 2, v39
	v_or_b32_e32 v45, v43, v32
	v_readlane_b32 s16, v254, 22
	v_lshlrev_b32_e32 v47, 1, v32
	v_mul_u32_u24_e32 v46, 0x90, v45
	v_mad_u32_u24 v112, v45, s5, v34
	v_add_u32_e32 v45, s16, v42
	v_or_b32_e32 v113, v43, v41
	v_lshlrev_b32_e32 v43, 4, v38
	v_add3_u32 v47, s16, v36, v47
	s_movk_i32 s16, 0x240
	v_add3_u32 v119, 0, v35, v43
	v_mul_lo_u32 v35, v38, s16
	v_or_b32_e32 v35, v35, v33
	s_movk_i32 s16, 0x48
	v_and_b32_e32 v40, -16, v37
	v_lshlrev_b32_e32 v35, 1, v35
	v_mul_lo_u32 v38, v104, s16
	v_readlane_b32 s16, v254, 29
	v_or_b32_e32 v40, v41, v40
	v_add_u32_e32 v120, 0, v35
	v_add_u32_e32 v35, s16, v35
	v_readlane_b32 s34, v254, 25
	v_readlane_b32 s35, v254, 13
	v_readlane_b32 s25, v254, 27
	v_add_u32_e32 v123, 0x2760, v35
	v_add_u32_e32 v124, 0x27f0, v35
	v_and_or_b32 v35, v36, 32, v32
	v_lshlrev_b32_e32 v36, 2, v40
	v_add3_u32 v107, s34, v46, v42
	v_and_b32_e32 v46, 0xffffff0f, v150
	v_add_u32_e32 v127, s25, v36
	v_add_u32_e32 v128, s35, v36
	v_or_b32_e32 v36, 1, v40
	v_cmp_eq_u32_e64 s[14:15], 0, v46
	v_or_b32_e32 v46, v43, v32
	v_lshlrev_b32_e32 v43, 2, v36
	v_and_b32_e32 v48, 0xc0, v150
	v_readlane_b32 s47, v254, 28
	v_add_u32_e32 v130, s25, v43
	v_add_u32_e32 v131, s35, v43
	v_or_b32_e32 v43, 2, v40
	v_add_u32_e32 v49, s47, v48
	v_lshlrev_b32_e32 v48, 2, v43
	s_movk_i32 s46, 0x90
	v_readlane_b32 s24, v254, 26
	v_or_b32_e32 v38, v38, v33
	v_add_u32_e32 v133, s25, v48
	v_add_u32_e32 v134, s35, v48
	v_or_b32_e32 v48, 3, v40
	v_add_u32_e32 v115, s17, v0
	v_lshl_add_u32 v121, v38, 1, 0
	v_mul_u32_u24_e32 v38, 0x110, v35
	v_lshl_add_u32 v125, v35, 2, s24
	v_lshl_add_u32 v126, v35, 1, s34
	v_cmp_le_i32_e64 s[16:17], v35, v40
	v_mul_lo_u32 v129, v40, s46
	v_cmp_le_i32_e64 s[18:19], v35, v36
	v_cmp_le_i32_e64 s[20:21], v35, v43
	v_cmp_le_i32_e64 s[22:23], v35, v48
	v_lshlrev_b32_e32 v50, 2, v48
	v_or_b32_e32 v35, 16, v35
	v_add_u32_e32 v117, s24, v0
	v_add_u32_e32 v118, s25, v0
	v_add_u32_e32 v132, 0x90, v129
	v_add_u32_e32 v135, 0x120, v129
	v_add_u32_e32 v137, s25, v50
	v_add_u32_e32 v139, 0x1b0, v129
	v_lshl_add_u32 v140, v35, 2, s24
	v_cmp_le_i32_e64 s[24:25], v35, v40
	v_lshlrev_b32_e32 v40, 1, v35
	v_add3_u32 v141, s34, v129, v40
	v_add3_u32 v142, s34, v132, v40
	v_add3_u32 v143, s34, v135, v40
	v_add3_u32 v144, s34, v139, v40
	v_readlane_b32 s34, v251, 56
	v_cmp_le_i32_e64 s[26:27], v35, v36
	v_cmp_le_i32_e64 s[28:29], v35, v43
	v_cmp_le_i32_e64 s[30:31], v35, v48
	v_and_b32_e32 v35, 0xffffffe0, v37
	v_or_b32_e32 v48, s34, v32
	v_add_u32_e32 v36, s34, v35
	v_mul_u32_u24_e32 v53, 0x90, v48
	v_or_b32_e32 v48, s34, v41
	v_readlane_b32 s34, v251, 54
	v_mul_u32_u24_e32 v54, 0x110, v48
	v_or_b32_e32 v37, 0x80, v32
	v_or_b32_e32 v48, s34, v32
	v_mul_u32_u24_e32 v55, 0x90, v48
	v_or_b32_e32 v48, s34, v41
	v_readlane_b32 s34, v251, 55
	v_mul_u32_u24_e32 v56, 0x110, v48
	v_mul_u32_u24_e32 v51, 0x90, v37
	v_or_b32_e32 v48, s34, v32
	v_mul_u32_u24_e32 v52, 0x110, v37
	v_lshlrev_b32_e32 v37, 2, v113
	v_mul_u32_u24_e32 v57, 0x90, v48
	v_or_b32_e32 v48, s34, v41
	v_readlane_b32 s34, v251, 57
	v_add_u32_e32 v116, s35, v0
; __device__ __forceinline__ void phase_mlstm_scan(const Params& p, const int tidx) {
;     ...
;   __syncthreads();
;   for (int e = tid; e < 144 * QSTR; e += NT) sC[e] = 0;
;   for (int e = tid; e < 144 * LSTR; e += NT) sVt[e] = 0;
;   __syncthreads();
;   if (tid < 64) sVt[128 * LSTR + tid] = 0x3F80;
;   f32x4 cacc[5];
; #pragma unroll
;   for (int i = 0; i < 5; i++) cacc[i] = f32x4{0.f, 0.f, 0.f, 0.f};
;   float mstate = -INFINITY;
;   u32x4 qv[2], kv[2], vv[2];
;   float gbc, glib, gpm;
;     ...
;   ML_LOAD(0);
;     ...
;       for (int r = 0; r < 4; r++) {
;         int t = ti * 16 + quad * 4 + r;
;         float den = s_den[t];
;         float dn = fmaxf(fabsf(den), __expf(-s_mt[t]));
;         float inv = __builtin_amdgcn_rcpf(dn);
;         int tau = tau0 + t;
;         int tt = dir ? (4095 - tau) : tau;
;         size_t rowoff = ((size_t)b * SEQ + tt) * NP + OFF_HDIR + dir * 512 + h * 128;
; #pragma unroll
;         for (int dj = 0; dj < 2; dj++) {
;           int dt = dbase + dg * 2 + dj;
;           P[rowoff + dt * 16 + l15] = f2bf(num[dj][r] * inv);
;         }
;       }
	v_add_u32_e32 v138, s35, v50
	v_or_b32_e32 v35, v36, v32
	v_add_u32_e32 v146, s35, v37
	v_mul_u32_u24_e32 v58, 0x110, v48
	v_or_b32_e32 v48, s34, v32
	v_or_b32_e32 v41, s34, v41
	v_readlane_b32 s34, v253, 26
	v_mul_lo_u32 v46, v46, s46
	v_mul_lo_u32 v40, v35, s46
	v_mul_lo_u32 v43, v35, s5
	v_or_b32_e32 v35, 16, v35
	v_readlane_b32 s35, v253, 27
	s_movk_i32 s12, 0x100
	v_add_u32_e32 v46, 0, v46
	v_mul_lo_u32 v50, v35, s46
	v_mul_lo_u32 v35, v35, s5
	v_add_u32_e32 v145, s47, v37
	v_ashrrev_i32_e32 v37, 31, v36
	v_mul_u32_u24_e32 v59, 0x90, v48
	v_mul_u32_u24_e32 v41, 0x110, v41
	v_mul_u32_u24_e32 v60, 0x90, v32
	v_mul_u32_u24_e32 v39, 0x440, v39
	v_lshl_add_u64 v[108:109], s[34:35], 0, v[0:1]
	s_movk_i32 s34, 0xfbf
	v_mov_b32_e32 v48, 0
	s_mov_b32 s0, 0
	v_cmp_gt_u32_e64 s[10:11], 64, v150
	v_cmp_gt_u32_e64 s[12:13], s12, v150
	v_or_b32_e32 v147, 64, v33
	v_bitop3_b32 v151, v150, s34, 63 bitop3:0x6c
	v_sub_u32_e32 v152, 0, v113
	v_mov_b32_e32 v188, 0xff800000
	v_add_u32_e32 v153, v34, v40
	v_add_u32_e32 v154, v45, v43
	v_add_u32_e32 v155, v44, v42
	v_add_u32_e32 v156, v34, v50
	v_add_u32_e32 v157, v45, v35
	v_add_u32_e32 v158, v34, v51
	v_add_u32_e32 v159, v45, v52
	v_add_u32_e32 v174, v49, v42
	v_lshlrev_b32_e32 v0, 1, v32
	v_lshlrev_b64 v[110:111], 1, v[36:37]
	v_add_u32_e32 v175, v46, v42
	v_add_u32_e32 v176, v34, v53
	v_add_u32_e32 v177, v47, v54
	v_add_u32_e32 v178, v34, v55
	v_add_u32_e32 v179, v47, v56
	v_add_u32_e32 v180, v34, v57
	v_add_u32_e32 v181, v47, v58
	v_add_u32_e32 v182, v34, v59
	v_add_u32_e32 v183, v47, v41
	v_add_u32_e32 v184, v34, v60
	v_add_u32_e32 v185, v47, v39
	v_add_u32_e32 v186, v34, v38
	s_mov_b32 s63, 0
	v_mov_b32_e32 v49, v48
	v_mov_b32_e32 v50, v48
	v_mov_b32_e32 v51, v48
	v_mov_b32_e32 v32, v48
	v_mov_b32_e32 v33, v48
	v_mov_b32_e32 v34, v48
	v_mov_b32_e32 v35, v48
	v_mov_b32_e32 v36, v48
	v_mov_b32_e32 v37, v48
	v_mov_b32_e32 v38, v48
	v_mov_b32_e32 v39, v48
	v_mov_b32_e32 v44, v48
	v_mov_b32_e32 v45, v48
	v_mov_b32_e32 v46, v48
	v_mov_b32_e32 v47, v48
	v_mov_b32_e32 v40, v48
	v_mov_b32_e32 v41, v48
	v_mov_b32_e32 v42, v48
	v_mov_b32_e32 v43, v48
	s_waitcnt vmcnt(0)
	s_branch .LBB0_207
.LBB0_206:
	s_or_b64 exec, exec, s[34:35]
	v_fma_f32 v54, v62, v74, v54
	v_fmac_f32_e32 v55, v63, v75
	s_waitcnt lgkmcnt(0)
	s_barrier
	ds_read_b128 v[62:65], v145
	ds_read_b128 v[66:69], v146
	v_fma_f32 v70, v60, v72, v52
	v_add_f32_e32 v52, s47, v188
	v_sub_f32_e32 v52, v52, v187
	v_mul_f32_e32 v52, 0x3fb8aa3b, v52
	v_exp_f32_e32 v60, v52
	s_waitcnt lgkmcnt(0)
	v_mul_f32_e32 v52, 0xbfb8aa3b, v66
	v_exp_f32_e32 v52, v52
	v_fma_f32 v61, v61, v73, v53
	v_max_f32_e64 v53, |v62|, |v62|
	v_fma_f32 v58, v74, v90, v58
	v_max_f32_e32 v52, v53, v52
	v_add_u32_e32 v74, s0, v152
	v_readlane_b32 s46, v251, 47
	v_rcp_f32_e32 v62, v52
	v_add_u32_e32 v66, s63, v113
	v_add_u32_e32 v52, 0xfff, v74
	v_readlane_b32 s47, v251, 48
	v_readlane_b32 s48, v251, 49
	v_fma_f32 v72, v72, v88, v56
	v_cndmask_b32_e64 v52, v52, v66, s[46:47]
	v_add_u32_e32 v56, s48, v52
	v_mov_b64_e32 v[52:53], s[94:95]
	v_readlane_b32 s38, v254, 30
	v_fma_f32 v73, v73, v89, v57
	v_mad_u64_u32 v[56:57], s[34:35], v56, s3, v[52:53]
	s_mov_b32 s65, s1
	v_readlane_b32 s39, v254, 31
	v_lshl_add_u64 v[56:57], v[56:57], 0, s[64:65]
	s_mov_b32 s39, s1
	v_lshl_add_u64 v[56:57], v[56:57], 0, s[38:39]
	v_lshl_add_u64 v[56:57], v[56:57], 0, v[0:1]
	v_mul_f32_e32 v70, v70, v62
	v_lshl_add_u64 v[56:57], v[56:57], 0, v[110:111]
	s_mov_b64 s[54:55], 0x2000
	s_movk_i32 s5, 0x2000
	v_fmac_f32_e32 v59, v75, v91
	v_cvt_pk_bf16_f32 v75, v70, s0
	v_lshl_add_u64 v[70:71], v[56:57], 0, s[54:55]
	v_add_co_u32_e32 v56, vcc, s5, v56
	s_add_i32 s63, s63, 64
	s_nop 0
	v_addc_co_u32_e32 v57, vcc, 0, v57, vcc
	global_store_short v[56:57], v75, off
	v_mul_f32_e32 v56, v72, v62
	v_cvt_pk_bf16_f32 v56, v56, s0
	global_store_short v[70:71], v56, off offset:32
	v_mul_f32_e32 v56, 0xbfb8aa3b, v67
	v_exp_f32_e32 v56, v56
	v_max_f32_e64 v57, |v63|, |v63|
	v_lshl_add_u64 v[108:109], v[108:109], 0, s[70:71]
	v_mov_b32_e32 v188, v187
	v_max_f32_e32 v56, v57, v56
	v_rcp_f32_e32 v67, v56
	v_add_u32_e32 v56, 1, v66
	v_add_u32_e32 v57, 0xffe, v74
	v_cndmask_b32_e64 v56, v57, v56, s[46:47]
	v_add_u32_e32 v56, s48, v56
	v_mad_u64_u32 v[56:57], s[34:35], v56, s3, v[52:53]
	v_lshl_add_u64 v[56:57], v[56:57], 0, s[64:65]
	v_lshl_add_u64 v[56:57], v[56:57], 0, s[38:39]
	v_lshl_add_u64 v[56:57], v[56:57], 0, v[0:1]
	v_lshl_add_u64 v[56:57], v[56:57], 0, v[110:111]
	v_mul_f32_e32 v61, v61, v67
	v_lshl_add_u64 v[62:63], v[56:57], 0, s[54:55]
	v_add_co_u32_e32 v56, vcc, s5, v56
	v_cvt_pk_bf16_f32 v61, v61, s0
	s_nop 0
	v_addc_co_u32_e32 v57, vcc, 0, v57, vcc
	global_store_short v[56:57], v61, off
	v_mul_f32_e32 v56, v73, v67
	v_cvt_pk_bf16_f32 v56, v56, s0
	global_store_short v[62:63], v56, off offset:32
	v_mul_f32_e32 v56, 0xbfb8aa3b, v68
	v_exp_f32_e32 v56, v56
	v_max_f32_e64 v57, |v64|, |v64|
	v_max_f32_e32 v56, v57, v56
	v_rcp_f32_e32 v61, v56
	v_add_u32_e32 v56, 2, v66
	v_add_u32_e32 v57, 0xffd, v74
	v_cndmask_b32_e64 v56, v57, v56, s[46:47]
	v_add_u32_e32 v56, s48, v56
	v_mad_u64_u32 v[56:57], s[34:35], v56, s3, v[52:53]
	v_lshl_add_u64 v[56:57], v[56:57], 0, s[64:65]
	v_lshl_add_u64 v[56:57], v[56:57], 0, s[38:39]
	v_lshl_add_u64 v[56:57], v[56:57], 0, v[0:1]
; __device__ __forceinline__ void phase_mlstm_scan(const Params& p, const int tidx) {
;     ...
;     const float bc = gbc, lib = glib, pm = gpm;
;     const float mt = bc + fmaxf(mstate, pm);
;     const float wint = __expf(bc + mstate - mt);
;     const float g = rdlane(bc, 63), pm63 = rdlane(pm, 63);
;     const float mnew = g + fmaxf(mstate, pm63);
;     const float decay = __expf(g + mstate - mnew);
;     const float wk = __expf(g + lib - mnew);
;     mstate = mnew;
;     if (w == 0) {
;       s_b[lane] = bc;
;       s_lib[lane] = lib;
;       s_mt[lane] = mt;
;       s_wint[lane] = wint;
;     }
;     ...
;       for (int r = 0; r < 4; r++) {
;         int t = ti * 16 + quad * 4 + r;
;         float den = s_den[t];
;         float dn = fmaxf(fabsf(den), __expf(-s_mt[t]));
;         float inv = __builtin_amdgcn_rcpf(dn);
;         int tau = tau0 + t;
;         int tt = dir ? (4095 - tau) : tau;
;         size_t rowoff = ((size_t)b * SEQ + tt) * NP + OFF_HDIR + dir * 512 + h * 128;
; #pragma unroll
;         for (int dj = 0; dj < 2; dj++) {
;           int dt = dbase + dg * 2 + dj;
;           P[rowoff + dt * 16 + l15] = f2bf(num[dj][r] * inv);
;         }
;       }
;     }
;     {
;       bf16x8 bfr[2];
; #pragma unroll
;       for (int k2 = 0; k2 < 2; k2++) bfr[k2] = *(const bf16x8*)(sKtw + (w * 16 + l15) * LSTR + k2 * 32 + quad * 8);
; #pragma unroll
;       for (int dj = 0; dj < 5; dj++) {
;         const int di = (dj == 4) ? 8 : (dbase + dj);
; #pragma unroll
;         for (int r = 0; r < 4; r++) cacc[dj][r] *= decay;
; #pragma unroll
;         for (int k2 = 0; k2 < 2; k2++) {
;           bf16x8 a = *(const bf16x8*)(sVt + (di * 16 + l15) * LSTR + k2 * 32 + quad * 8);
;           cacc[dj] = __builtin_amdgcn_mfma_f32_16x16x32_bf16(a, bfr[k2], cacc[dj], 0, 0, 0);
;         }
; #pragma unroll
;         for (int r = 0; r < 4; r++) sC[(di * 16 + quad * 4 + r) * QSTR + w * 16 + l15] = f2bf(cacc[dj][r]);
;       }
;     }
	v_lshl_add_u64 v[56:57], v[56:57], 0, v[110:111]
	v_mul_f32_e32 v54, v54, v61
	v_lshl_add_u64 v[62:63], v[56:57], 0, s[54:55]
	v_add_co_u32_e32 v56, vcc, s5, v56
	v_cvt_pk_bf16_f32 v54, v54, s0
	s_nop 0
	v_addc_co_u32_e32 v57, vcc, 0, v57, vcc
	global_store_short v[56:57], v54, off
	v_mul_f32_e32 v54, v58, v61
	v_cvt_pk_bf16_f32 v54, v54, s0
	global_store_short v[62:63], v54, off offset:32
	v_mul_f32_e32 v54, 0xbfb8aa3b, v69
	v_exp_f32_e32 v54, v54
	v_max_f32_e64 v56, |v65|, |v65|
	v_add_u32_e32 v57, 0xffc, v74
	v_pk_mul_f32 v[48:49], v[48:49], v[60:61] op_sel_hi:[1,0]
	v_max_f32_e32 v54, v56, v54
	v_rcp_f32_e32 v56, v54
	v_add_u32_e32 v54, 3, v66
	v_cndmask_b32_e64 v54, v57, v54, s[46:47]
	v_add_u32_e32 v54, s48, v54
	v_mad_u64_u32 v[52:53], s[34:35], v54, s3, v[52:53]
	v_lshl_add_u64 v[52:53], v[52:53], 0, s[64:65]
	v_lshl_add_u64 v[52:53], v[52:53], 0, s[38:39]
	v_lshl_add_u64 v[52:53], v[52:53], 0, v[0:1]
	v_mul_f32_e32 v54, v55, v56
	v_lshl_add_u64 v[52:53], v[52:53], 0, v[110:111]
	v_cvt_pk_bf16_f32 v57, v54, s0
	v_lshl_add_u64 v[54:55], v[52:53], 0, s[54:55]
	v_add_co_u32_e32 v52, vcc, s5, v52
	v_pk_mul_f32 v[50:51], v[50:51], v[60:61] op_sel_hi:[1,0]
	s_nop 0
	v_addc_co_u32_e32 v53, vcc, 0, v53, vcc
	global_store_short v[52:53], v57, off
	v_mul_f32_e32 v52, v59, v56
	v_cvt_pk_bf16_f32 v52, v52, s0
	global_store_short v[54:55], v52, off offset:32
	ds_read_b128 v[56:59], v175 offset:55552
	ds_read_b128 v[52:55], v175 offset:55616
	ds_read_b128 v[190:193], v176 offset:34816
	ds_read_b128 v[194:197], v176 offset:34880
	ds_read_b128 v[198:201], v178 offset:34816
	ds_read_b128 v[202:205], v178 offset:34880
	ds_read_b128 v[206:209], v180 offset:34816
	ds_read_b128 v[210:213], v180 offset:34880
	ds_read_b128 v[214:217], v182 offset:34816
	ds_read_b128 v[218:221], v182 offset:34880
	ds_read_b128 v[222:225], v184 offset:53248
	ds_read_b128 v[226:229], v184 offset:53312
	s_mov_b32 s34, s38
	v_writelane_b32 v254, s34, 30
	v_writelane_b32 v254, s35, 31
	v_pk_mul_f32 v[32:33], v[32:33], v[60:61] op_sel_hi:[1,0]
	v_pk_mul_f32 v[34:35], v[34:35], v[60:61] op_sel_hi:[1,0]
	v_pk_mul_f32 v[36:37], v[36:37], v[60:61] op_sel_hi:[1,0]
	v_pk_mul_f32 v[38:39], v[38:39], v[60:61] op_sel_hi:[1,0]
	v_pk_mul_f32 v[44:45], v[44:45], v[60:61] op_sel_hi:[1,0]
	v_pk_mul_f32 v[46:47], v[46:47], v[60:61] op_sel_hi:[1,0]
	v_pk_mul_f32 v[40:41], v[40:41], v[60:61] op_sel_hi:[1,0]
	v_pk_mul_f32 v[42:43], v[42:43], v[60:61] op_sel_hi:[1,0]
	s_waitcnt lgkmcnt(9)
	v_mfma_f32_16x16x32_bf16 v[48:51], v[190:193], v[56:59], v[48:51]
	s_waitcnt lgkmcnt(8)
	v_mfma_f32_16x16x32_bf16 v[48:51], v[194:197], v[52:55], v[48:51]
	s_waitcnt lgkmcnt(7)
	v_mfma_f32_16x16x32_bf16 v[32:35], v[198:201], v[56:59], v[32:35]
	s_waitcnt lgkmcnt(6)
	v_mfma_f32_16x16x32_bf16 v[32:35], v[202:205], v[52:55], v[32:35]
	s_waitcnt lgkmcnt(5)
	v_mfma_f32_16x16x32_bf16 v[36:39], v[206:209], v[56:59], v[36:39]
	s_waitcnt lgkmcnt(4)
	v_mfma_f32_16x16x32_bf16 v[36:39], v[210:213], v[52:55], v[36:39]
	s_waitcnt lgkmcnt(3)
	v_mfma_f32_16x16x32_bf16 v[44:47], v[214:217], v[56:59], v[44:47]
	s_waitcnt lgkmcnt(2)
	v_mfma_f32_16x16x32_bf16 v[44:47], v[218:221], v[52:55], v[44:47]
	s_waitcnt lgkmcnt(1)
	v_mfma_f32_16x16x32_bf16 v[40:43], v[222:225], v[56:59], v[40:43]
	s_waitcnt lgkmcnt(0)
	v_mfma_f32_16x16x32_bf16 v[40:43], v[226:229], v[52:55], v[40:43]
	s_sub_i32 s0, s0, 64
	s_cmpk_eq_i32 s63, 0x1000
	v_cvt_pk_bf16_f32 v230, v48, s0
	v_cvt_pk_bf16_f32 v231, v49, s0
	v_cvt_pk_bf16_f32 v232, v50, s0
	v_cvt_pk_bf16_f32 v233, v51, s0
	ds_write_b16 v177, v230
	ds_write_b16 v177, v231 offset:272
	ds_write_b16 v177, v232 offset:544
	ds_write_b16 v177, v233 offset:816
	v_cvt_pk_bf16_f32 v234, v32, s0
	v_cvt_pk_bf16_f32 v235, v33, s0
	v_cvt_pk_bf16_f32 v236, v34, s0
	v_cvt_pk_bf16_f32 v237, v35, s0
	ds_write_b16 v179, v234
	ds_write_b16 v179, v235 offset:272
	ds_write_b16 v179, v236 offset:544
	ds_write_b16 v179, v237 offset:816
	v_cvt_pk_bf16_f32 v238, v36, s0
	v_cvt_pk_bf16_f32 v239, v37, s0
	v_cvt_pk_bf16_f32 v240, v38, s0
	v_cvt_pk_bf16_f32 v241, v39, s0
	ds_write_b16 v181, v238
	ds_write_b16 v181, v239 offset:272
	ds_write_b16 v181, v240 offset:544
	ds_write_b16 v181, v241 offset:816
	v_cvt_pk_bf16_f32 v242, v44, s0
	v_cvt_pk_bf16_f32 v243, v45, s0
	v_cvt_pk_bf16_f32 v244, v46, s0
	v_cvt_pk_bf16_f32 v245, v47, s0
	ds_write_b16 v183, v242
	ds_write_b16 v183, v243 offset:272
	ds_write_b16 v183, v244 offset:544
	ds_write_b16 v183, v245 offset:816
	s_nop 3
	v_cvt_pk_bf16_f32 v246, v40, s0
	v_cvt_pk_bf16_f32 v247, v41, s0
	v_cvt_pk_bf16_f32 v248, v42, s0
	v_cvt_pk_bf16_f32 v249, v43, s0
	ds_write_b16 v185, v246 offset:34816
	ds_write_b16 v185, v247 offset:35088
	ds_write_b16 v185, v248 offset:35360
	ds_write_b16 v185, v249 offset:35632
	s_waitcnt lgkmcnt(0)
	s_barrier
	s_cbranch_scc1 .LBB0_247
.LBB0_207:
	s_waitcnt vmcnt(10)
	v_readlane_b32 s47, v114, 63
	s_waitcnt vmcnt(8)
	v_readlane_b32 s49, v136, 63
	v_max_f32_e32 v52, v188, v188
	s_and_saveexec_b64 s[34:35], s[10:11]
	s_cbranch_execz .LBB0_209
	v_max_f32_e32 v54, v136, v136
	v_max_f32_e32 v54, v52, v54
	v_add_f32_e32 v53, v188, v114
	v_add_f32_e32 v54, v114, v54
	v_sub_f32_e32 v53, v53, v54
	v_mul_f32_e32 v53, 0x3fb8aa3b, v53
	v_exp_f32_e32 v53, v53
	ds_write_b32 v118, v114
	ds_write_b32 v117, v122
	ds_write_b32 v116, v54
	ds_write_b32 v115, v53

; __device__ __forceinline__ void phase_mlstm_scan(const Params& p, const int tidx) {
;     ...
;     {
;       const int ti = w >> 1;
; #pragma unroll
;       for (int jj = 0; jj < 2; jj++) {
;         const int sj = (w & 1) * 2 + jj;
;         f32x4 acc = {0.f, 0.f, 0.f, 0.f};
; #pragma unroll
;         for (int kk = 0; kk < 128; kk += 32) {
;           bf16x8 a = *(const bf16x8*)(sQ + (ti * 16 + l15) * QSTR + kk + quad * 8);
;           bf16x8 bb = *(const bf16x8*)(sK + (sj * 16 + l15) * QSTR + kk + quad * 8);
;           acc = __builtin_amdgcn_mfma_f32_16x16x32_bf16(a, bb, acc, 0, 0, 0);
;         }
;         int s = sj * 16 + l15;
;         float libs = s_lib[s];
; #pragma unroll
;         for (int r = 0; r < 4; r++) {
;           int t = ti * 16 + quad * 4 + r;
;           float v = (s <= t) ? acc[r] * __expf(s_b[t] - s_mt[t] + libs) : 0.f;
;           sS[t * LSTR + s] = f2bf(v);
;         }
;       }
;     }
;     __syncthreads();
;     {
;       const int ti = w & 3, dg = w >> 2;
;       const int nd = dg ? 2 : 3;
;       f32x4 num[3];
; #pragma unroll
;       for (int dj = 0; dj < 3; dj++) {
;         f32x4 a1 = {0.f, 0.f, 0.f, 0.f}, a2 = {0.f, 0.f, 0.f, 0.f};
;         const int dt = (dj == 2) ? 8 : (dbase + dg * 2 + dj);
;         if (dj < nd) {
; #pragma unroll
;           for (int kk = 0; kk < 64; kk += 32) {
;             bf16x8 a = *(const bf16x8*)(sS + (ti * 16 + l15) * LSTR + kk + quad * 8);
;             bf16x8 bb = *(const bf16x8*)(sVt + (dt * 16 + l15) * LSTR + kk + quad * 8);
;             a1 = __builtin_amdgcn_mfma_f32_16x16x32_bf16(a, bb, a1, 0, 0, 0);
;           }
; #pragma unroll
;           for (int kk = 0; kk < 128; kk += 32) {
;             bf16x8 a = *(const bf16x8*)(sQ + (ti * 16 + l15) * QSTR + kk + quad * 8);
;             bf16x8 bb = *(const bf16x8*)(sC + (dt * 16 + l15) * QSTR + kk + quad * 8);
;             a2 = __builtin_amdgcn_mfma_f32_16x16x32_bf16(a, bb, a2, 0, 0, 0);
;           }
;         }
; #pragma unroll
;         for (int r = 0; r < 4; r++) num[dj][r] = a1[r] + s_wint[ti * 16 + quad * 4 + r] * a2[r];
.LBB0_227:
	s_waitcnt lgkmcnt(0)
	s_barrier
	ds_read_b128 v[190:193], v106
	ds_read_b128 v[194:197], v186 offset:17408
	ds_read_b128 v[198:201], v106 offset:64
	ds_read_b128 v[202:205], v186 offset:17472
	ds_read_b128 v[206:209], v106 offset:128
	ds_read_b128 v[210:213], v186 offset:17536
	ds_read_b128 v[214:217], v106 offset:192
	ds_read_b128 v[218:221], v186 offset:17600
	ds_read_b128 v[222:225], v186 offset:21760
	ds_read_b128 v[226:229], v186 offset:21824
	ds_read_b128 v[230:233], v186 offset:21888
	ds_read_b128 v[234:237], v186 offset:21952
	s_waitcnt lgkmcnt(10)
	v_mfma_f32_16x16x32_bf16 v[52:55], v[190:193], v[194:197], 0
	s_waitcnt lgkmcnt(8)
	v_mfma_f32_16x16x32_bf16 v[52:55], v[198:201], v[202:205], v[52:55]
	s_waitcnt lgkmcnt(6)
	v_mfma_f32_16x16x32_bf16 v[52:55], v[206:209], v[210:213], v[52:55]
	s_waitcnt lgkmcnt(4)
	v_mfma_f32_16x16x32_bf16 v[52:55], v[214:217], v[218:221], v[52:55]
	ds_read_b32 v238, v125
	ds_read_b32 v239, v140
	ds_read_b32 v240, v127
	ds_read_b32 v241, v128
	ds_read_b32 v242, v130
	ds_read_b32 v243, v131
	ds_read_b32 v244, v133
	ds_read_b32 v245, v134
	ds_read_b32 v246, v137
	ds_read_b32 v247, v138
	s_waitcnt lgkmcnt(13)
	v_mfma_f32_16x16x32_bf16 v[56:59], v[190:193], v[222:225], 0
	s_waitcnt lgkmcnt(12)
	v_mfma_f32_16x16x32_bf16 v[56:59], v[198:201], v[226:229], v[56:59]
	s_waitcnt lgkmcnt(11)
	v_mfma_f32_16x16x32_bf16 v[56:59], v[206:209], v[230:233], v[56:59]
	s_waitcnt lgkmcnt(10)
	v_mfma_f32_16x16x32_bf16 v[56:59], v[214:217], v[234:237], v[56:59]
	s_waitcnt lgkmcnt(0)
	v_sub_f32_e32 v240, v240, v241
	v_sub_f32_e32 v242, v242, v243
	v_sub_f32_e32 v244, v244, v245
	v_sub_f32_e32 v246, v246, v247
	v_add_f32_e32 v190, v238, v240
	v_add_f32_e32 v194, v239, v240
	v_add_f32_e32 v191, v238, v242
	v_add_f32_e32 v195, v239, v242
	v_add_f32_e32 v192, v238, v244
	v_add_f32_e32 v196, v239, v244
	v_add_f32_e32 v193, v238, v246
	v_add_f32_e32 v197, v239, v246
	v_mul_f32_e32 v190, 0x3fb8aa3b, v190
	v_mul_f32_e32 v194, 0x3fb8aa3b, v194
	v_mul_f32_e32 v191, 0x3fb8aa3b, v191
	v_mul_f32_e32 v195, 0x3fb8aa3b, v195
	v_mul_f32_e32 v192, 0x3fb8aa3b, v192
	v_mul_f32_e32 v196, 0x3fb8aa3b, v196
	v_mul_f32_e32 v193, 0x3fb8aa3b, v193
	v_mul_f32_e32 v197, 0x3fb8aa3b, v197
	v_exp_f32_e32 v190, v190
	v_exp_f32_e32 v194, v194
	v_exp_f32_e32 v191, v191
	v_exp_f32_e32 v195, v195
	v_exp_f32_e32 v192, v192
	v_exp_f32_e32 v196, v196
	v_exp_f32_e32 v193, v193
	v_exp_f32_e32 v197, v197
	v_mul_f32_e32 v190, v52, v190
	v_mul_f32_e32 v191, v53, v191
	v_mul_f32_e32 v192, v54, v192
	v_mul_f32_e32 v193, v55, v193
	v_mul_f32_e32 v194, v56, v194
	v_mul_f32_e32 v195, v57, v195
	v_mul_f32_e32 v196, v58, v196
	v_mul_f32_e32 v197, v59, v197
	v_cvt_pk_bf16_f32 v190, v190, s0
	v_cvt_pk_bf16_f32 v194, v194, s0
	v_cvt_pk_bf16_f32 v191, v191, s0
	v_cvt_pk_bf16_f32 v195, v195, s0
	v_cvt_pk_bf16_f32 v192, v192, s0
	v_cvt_pk_bf16_f32 v196, v196, s0
	v_cvt_pk_bf16_f32 v193, v193, s0
	v_cvt_pk_bf16_f32 v197, v197, s0
	v_cndmask_b32_e64 v190, 0, v190, s[16:17]
	v_cndmask_b32_e64 v194, 0, v194, s[24:25]
	v_cndmask_b32_e64 v191, 0, v191, s[18:19]
	v_cndmask_b32_e64 v195, 0, v195, s[26:27]
	v_cndmask_b32_e64 v192, 0, v192, s[20:21]
	v_cndmask_b32_e64 v196, 0, v196, s[28:29]
	v_cndmask_b32_e64 v193, 0, v193, s[22:23]
	v_cndmask_b32_e64 v197, 0, v197, s[30:31]
	v_add_u32_e32 v198, v126, v129
	v_add_u32_e32 v199, v126, v132
	v_add_u32_e32 v200, v126, v135
	v_add_u32_e32 v201, v126, v139
	ds_write_b16 v198, v190
	ds_write_b16 v199, v191
	ds_write_b16 v200, v192
	ds_write_b16 v201, v193
	ds_write_b16 v141, v194
	ds_write_b16 v142, v195
	ds_write_b16 v143, v196
	ds_write_b16 v144, v197
	s_waitcnt lgkmcnt(0)
	s_barrier
	ds_read_b128 v[80:83], v112
	ds_read_b128 v[198:201], v154
	ds_read_b128 v[76:79], v112 offset:64
	ds_read_b128 v[202:205], v154 offset:64
	ds_read_b128 v[84:87], v112 offset:128
	ds_read_b128 v[206:209], v154 offset:128
	ds_read_b128 v[92:95], v112 offset:192
	ds_read_b128 v[210:213], v154 offset:192
	ds_read_b128 v[68:71], v107
	ds_read_b128 v[190:193], v153 offset:34816
	ds_read_b128 v[64:67], v107 offset:64
	ds_read_b128 v[194:197], v153 offset:34880
	s_waitcnt lgkmcnt(10)
	v_mfma_f32_16x16x32_bf16 v[60:63], v[80:83], v[198:201], 0
	s_waitcnt lgkmcnt(8)
	v_mfma_f32_16x16x32_bf16 v[60:63], v[76:79], v[202:205], v[60:63]
	s_waitcnt lgkmcnt(6)
	v_mfma_f32_16x16x32_bf16 v[60:63], v[84:87], v[206:209], v[60:63]
	s_waitcnt lgkmcnt(4)
	v_mfma_f32_16x16x32_bf16 v[60:63], v[92:95], v[210:213], v[60:63]
	ds_read_b128 v[222:225], v157
	ds_read_b128 v[226:229], v157 offset:64
	ds_read_b128 v[230:233], v157 offset:128
	ds_read_b128 v[234:237], v157 offset:192
	ds_read_b128 v[214:217], v156 offset:34816
	ds_read_b128 v[218:221], v156 offset:34880
	ds_read_b128 v[72:75], v155
	s_waitcnt lgkmcnt(9)
	v_mfma_f32_16x16x32_bf16 v[52:55], v[68:71], v[190:193], 0
	s_waitcnt lgkmcnt(7)
	v_mfma_f32_16x16x32_bf16 v[52:55], v[64:67], v[194:197], v[52:55]
	s_waitcnt lgkmcnt(6)
	v_mfma_f32_16x16x32_bf16 v[88:91], v[80:83], v[222:225], 0
	s_waitcnt lgkmcnt(5)
	v_mfma_f32_16x16x32_bf16 v[88:91], v[76:79], v[226:229], v[88:91]
	s_waitcnt lgkmcnt(4)
	v_mfma_f32_16x16x32_bf16 v[88:91], v[84:87], v[230:233], v[88:91]
	s_waitcnt lgkmcnt(3)
	v_mfma_f32_16x16x32_bf16 v[88:91], v[92:95], v[234:237], v[88:91]
	s_waitcnt lgkmcnt(0)
	v_mfma_f32_16x16x32_bf16 v[56:59], v[68:71], v[214:217], 0
	v_mfma_f32_16x16x32_bf16 v[56:59], v[64:67], v[218:221], v[56:59]
	v_mov_b32_e32 v100, 0
	v_mov_b32_e32 v101, 0
	v_mov_b32_e32 v102, 0
	v_mov_b32_e32 v103, 0
	v_mov_b32_e32 v96, 0
	v_mov_b32_e32 v97, 0
	v_mov_b32_e32 v98, 0
	v_mov_b32_e32 v99, 0
	s_and_saveexec_b64 s[34:35], s[12:13]
	s_cbranch_execz .LBB0_245
	ds_read_b128 v[198:201], v159
	ds_read_b128 v[202:205], v159 offset:64
	ds_read_b128 v[206:209], v159 offset:128
	ds_read_b128 v[210:213], v159 offset:192
	ds_read_b128 v[190:193], v158 offset:34816
	ds_read_b128 v[194:197], v158 offset:34880
	s_waitcnt lgkmcnt(5)
	v_mfma_f32_16x16x32_bf16 v[100:103], v[80:83], v[198:201], 0
	s_waitcnt lgkmcnt(4)
	v_mfma_f32_16x16x32_bf16 v[100:103], v[76:79], v[202:205], v[100:103]
	s_waitcnt lgkmcnt(3)
	v_mfma_f32_16x16x32_bf16 v[100:103], v[84:87], v[206:209], v[100:103]
	s_waitcnt lgkmcnt(2)
	v_mfma_f32_16x16x32_bf16 v[100:103], v[92:95], v[210:213], v[100:103]
	s_waitcnt lgkmcnt(1)
	v_mfma_f32_16x16x32_bf16 v[96:99], v[68:71], v[190:193], 0
	s_waitcnt lgkmcnt(0)
	v_mfma_f32_16x16x32_bf16 v[96:99], v[64:67], v[194:197], v[96:99]
